# GA loop-edge edit: next-tile global loads moved from the post-barrier head into the previous copy's trailing MFMA shadow
# baseline (speedup 1.0000x reference)
.LBB0_1273:
	s_andn2_b64 vcc, exec, s[0:1]
	s_cbranch_vccnz .LBB0_1287
	s_lshl_b32 s0, s22, 1
	s_addk_i32 s0, 0xfeb0
	v_mov_b32_e32 v20, v201
	v_add_u32_e32 v8, s0, v149
	v_lshlrev_b32_e32 v0, 6, v8
	v_lshrrev_b32_e32 v6, 1, v20
	v_and_b32_e32 v2, 32, v6
	s_movk_i32 s0, 0xfc0
	v_ashrrev_i32_e32 v106, 7, v8
	v_bfe_u32 v5, v8, 6, 1
	v_and_or_b32 v0, v0, s0, v2
	v_mov_b64_e32 v[2:3], s[42:43]
	s_mov_b32 s0, 0x220000
	v_mad_i64_i32 v[2:3], s[0:1], v106, s0, v[2:3]
	v_lshlrev_b32_e32 v4, 7, v5
	v_and_or_b32 v110, v6, 64, v4
	v_mov_b64_e32 v[6:7], s[58:59]
	s_mov_b32 s0, 0x110000
	v_add_u32_e32 v108, 0x100, v0
	v_lshlrev_b32_e32 v0, 1, v110
	v_mad_i64_i32 v[6:7], s[0:1], v106, s0, v[6:7]
	v_and_b32_e32 v107, 15, v20
	v_bfe_u32 v21, v20, 4, 2
	v_lshl_add_u64 v[2:3], v[2:3], 0, v[0:1]
	v_lshlrev_b32_e32 v0, 6, v5
	v_mov_b32_e32 v5, v1
	s_movk_i32 s0, 0xff80
	v_lshl_add_u64 v[4:5], v[6:7], 0, v[4:5]
	v_and_or_b32 v6, v8, s0, v0
	v_or_b32_e32 v7, v108, v107
	v_lshlrev_b32_e32 v0, 4, v21
	v_lshl_add_u64 v[2:3], v[2:3], 0, v[0:1]
	v_lshlrev_b32_e32 v0, 9, v7
	v_lshl_add_u64 v[2:3], v[2:3], 0, v[0:1]
	s_movk_i32 s0, 0x2000
	global_load_dwordx4 v[46:49], v[2:3], off
	global_load_dwordx4 v[42:45], v[2:3], off offset:64
	v_add_co_u32_e32 v2, vcc, s0, v2
	v_and_b32_e32 v22, 7, v20
	s_nop 0
	v_addc_co_u32_e32 v3, vcc, 0, v3, vcc
	global_load_dwordx4 v[50:53], v[2:3], off
	global_load_dwordx4 v[54:57], v[2:3], off offset:64
	v_mov_b64_e32 v[2:3], s[44:45]
	v_bfe_u32 v126, v20, 3, 5
	v_lshlrev_b32_e32 v114, 4, v22
	v_mov_b32_e32 v115, v1
	v_mad_i64_i32 v[2:3], s[0:1], v6, s85, v[2:3]
	v_lshl_add_u64 v[116:117], v[4:5], 0, v[114:115]
	v_lshlrev_b32_e32 v0, 8, v126
	v_or_b32_e32 v23, 32, v126
	v_lshl_add_u64 v[18:19], v[2:3], 0, v[114:115]
	v_lshl_add_u64 v[2:3], v[116:117], 0, v[0:1]
	v_lshlrev_b32_e32 v0, 8, v23
	v_mad_u64_u32 v[6:7], s[0:1], v126, s85, v[18:19]
	v_lshl_add_u64 v[10:11], v[116:117], 0, v[0:1]
	v_mad_u64_u32 v[14:15], s[0:1], v23, s85, v[18:19]
	v_mov_b32 v122, 0xc2800000
	global_load_dwordx4 v[2:5], v[2:3], off
	s_nop 0
	global_load_dwordx4 v[6:9], v[6:7], off
	s_nop 0
	global_load_dwordx4 v[10:13], v[10:11], off
	s_nop 0
	global_load_dwordx4 v[14:17], v[14:15], off
	v_lshrrev_b32_e32 v26, 3, v20
	v_lshrrev_b32_e32 v25, 4, v20
	v_xor_b32_e32 v20, v26, v20
	v_lshlrev_b32_e32 v20, 4, v20
	v_and_b32_e32 v132, 0x70, v20
	v_lshlrev_b32_e32 v112, 3, v21
	v_lshlrev_b32_e32 v127, 7, v126
	v_bitop3_b32 v21, v21, v22, 4 bitop3:0x36
	v_add_u32_e32 v20, v150, v132
	v_and_b32_e32 v24, 64, v208
	v_mul_u32_u24_e32 v128, 0x90, v126
	v_lshlrev_b32_e32 v131, 7, v23
	v_lshlrev_b32_e32 v129, 4, v21
	v_add_u32_e32 v21, v20, v127
	v_xor_b32_e32 v0, 16, v208
	v_bitop3_b32 v25, v25, v22, 3 bitop3:0x6c
	v_add3_u32 v22, v150, v114, v128
	v_add_u32_e32 v20, v20, v131
	v_lshlrev_b32_e32 v130, 4, v25
	v_mov_b32_e32 v38, 0
	s_mov_b32 s0, 0
	v_lshlrev_b32_e32 v115, 7, v107
	v_mov_b32_e32 v123, v122
	v_mov_b32_e32 v165, 0
	v_mov_b32_e32 v152, 0x42800000
	v_mov_b32_e32 v153, v152
	v_mov_b32_e32 v154, v152
	v_mov_b32_e32 v155, v152
	v_mov_b32_e32 v156, v152
	v_mov_b32_e32 v157, v152
	v_mov_b32_e32 v158, v152
	v_mov_b32_e32 v159, v152
	v_mul_u32_u24_e32 v109, 0x90, v107
	v_mov_b32_e32 v39, v38
	v_mov_b32_e32 v40, v38
	v_mov_b32_e32 v41, v38
	v_mov_b32_e32 v34, v38
	v_mov_b32_e32 v35, v38
	v_mov_b32_e32 v36, v38
	v_mov_b32_e32 v37, v38
	s_waitcnt vmcnt(0) lgkmcnt(0)
	ds_write_b128 v21, v[2:5]
	ds_write_b128 v22, v[6:9] offset:8192
	ds_write_b128 v20, v[10:13]
	ds_write_b128 v22, v[14:17] offset:12800
	v_add_u32_e32 v2, 64, v24
	v_cmp_lt_i32_e32 vcc, v0, v2
	v_mov_b32_e32 v3, v1
	s_waitcnt lgkmcnt(0)
	v_cndmask_b32_e32 v0, v208, v0, vcc
	v_lshlrev_b32_e32 v111, 2, v0
	v_xor_b32_e32 v0, 32, v208
	v_cmp_lt_i32_e32 vcc, v0, v2
	v_mov_b32_e32 v2, v1
	s_barrier
	v_cndmask_b32_e32 v0, v208, v0, vcc
	v_lshlrev_b32_e32 v113, 2, v0
	v_mul_u32_u24_e32 v0, 0x1100, v126
	v_lshlrev_b32_e32 v0, 1, v0
	v_lshl_add_u64 v[120:121], v[18:19], 0, v[0:1]
	v_mov_b32_e32 v0, v1
	v_mov_b64_e32 v[20:21], v[2:3]
	v_mov_b64_e32 v[24:25], v[2:3]
	v_mov_b64_e32 v[28:29], v[2:3]
	v_mov_b64_e32 v[32:33], v[2:3]
	v_mov_b64_e32 v[12:13], v[2:3]
	v_mov_b64_e32 v[16:17], v[2:3]
	v_mov_b64_e32 v[8:9], v[2:3]
	v_mov_b64_e32 v[18:19], v[0:1]
	v_mov_b64_e32 v[22:23], v[0:1]
	v_mov_b64_e32 v[26:27], v[0:1]
	v_mov_b64_e32 v[30:31], v[0:1]
	v_mov_b64_e32 v[10:11], v[0:1]
	v_mov_b64_e32 v[14:15], v[0:1]
	v_mov_b64_e32 v[6:7], v[0:1]
	v_mov_b64_e32 v[4:5], v[2:3]
	v_mov_b64_e32 v[2:3], v[0:1]
	v_add_u32_e32 v170, v150, v115
	v_add_u32_e32 v171, v170, v129
	v_add_u32_e32 v170, v170, v130
	v_add3_u32 v172, v150, v109, v112
	v_add_u32_e32 v173, 0x2800, v172
	v_add_u32_e32 v174, 0x6400, v172
	v_add_u32_e32 v175, 0x6c00, v172
	v_add_u32_e32 v176, 0x3000, v172
	v_add_u32_e32 v177, 0x3800, v172
	v_add_u32_e32 v178, 0x7400, v172
	v_add_u32_e32 v179, 0x7c00, v172
	v_add_u32_e32 v172, 0x2000, v172
	v_add_u32_e32 v180, v150, v132
	v_add_u32_e32 v181, v180, v131
	v_add_u32_e32 v180, v180, v127
	v_add3_u32 v182, v150, v114, v128
	v_lshlrev_b32_e32 v164, 8, v126
	v_lshl_add_u64 v[184:185], v[116:117], 0, v[164:165]
	s_mov_b64 s[2:3], 0x2000
	v_lshl_add_u64 v[186:187], v[184:185], 0, s[2:3]
	s_mov_b64 s[2:3], 0x44000
	v_lshl_add_u64 v[188:189], v[120:121], 0, s[2:3]
	v_mov_b32_e32 v190, s36
	v_mov_b32_e32 v191, s36
	v_mov_b32_e32 v192, s36
	v_mov_b32_e32 v193, s36
	s_mov_b32 s1, 1
	v_lshl_or_b32 v68, s1, 6, v126
	v_lshlrev_b32_e32 v0, 8, v68
	s_lshl_b32 s56, s1, 7
	v_lshl_add_u64 v[58:59], v[116:117], 0, v[0:1]
	v_lshl_add_u64 v[66:67], v[120:121], 0, s[56:57]
	v_or_b32_e32 v0, 32, v68
	s_mov_b32 s1, 0x44000
	v_lshlrev_b64 v[68:69], 8, v[0:1]
	v_add_co_u32_e32 v70, vcc, s1, v66
	v_lshl_add_u64 v[68:69], v[116:117], 0, v[68:69]
	s_nop 0
	v_addc_co_u32_e32 v71, vcc, 0, v67, vcc
	global_load_dwordx4 v[58:61], v[58:59], off
	s_nop 0
	global_load_dwordx4 v[62:65], v[66:67], off
	s_nop 0
	global_load_dwordx4 v[66:69], v[68:69], off
	s_nop 0
	global_load_dwordx4 v[70:73], v[70:71], off
	s_mov_b32 s1, 2
	s_lshl_b32 s2, s1, 14
	s_lshl_b32 s56, s1, 7
	v_lshl_add_u64 v[228:229], v[184:185], 0, s[2:3]
	v_lshl_add_u64 v[236:237], v[120:121], 0, s[56:57]
	v_lshl_add_u64 v[238:239], v[186:187], 0, s[2:3]
	v_lshl_add_u64 v[240:241], v[188:189], 0, s[56:57]
	global_load_dwordx4 v[228:231], v[228:229], off
	global_load_dwordx4 v[232:235], v[236:237], off
	global_load_dwordx4 v[236:239], v[238:239], off
	global_load_dwordx4 v[240:243], v[240:241], off
.LBB0_1275:
	s_add_i32 s0, s0, 1
	ds_read_b128 v[74:77], v170
	ds_read_b128 v[82:85], v170 offset:2048
	ds_read_b128 v[86:89], v171
	ds_read_b128 v[98:101], v171 offset:2048
	s_setprio 1
	s_waitcnt lgkmcnt(0)
	v_mfma_f32_16x16x32_bf16 v[78:81], v[74:77], v[46:49], v[152:155]
	v_mfma_f32_16x16x32_bf16 v[74:77], v[74:77], v[50:53], v[156:159]
	v_mfma_f32_16x16x32_bf16 v[94:97], v[86:89], v[42:45], v[78:81]
	v_mfma_f32_16x16x32_bf16 v[78:81], v[86:89], v[54:57], v[74:77]
	v_mfma_f32_16x16x32_bf16 v[74:77], v[82:85], v[46:49], v[152:155]
	v_mfma_f32_16x16x32_bf16 v[90:93], v[98:101], v[42:45], v[74:77]
	v_mfma_f32_16x16x32_bf16 v[74:77], v[82:85], v[50:53], v[156:159]
	ds_read_b128 v[82:85], v170 offset:4096
	ds_read_b128 v[134:137], v170 offset:6144
	v_mfma_f32_16x16x32_bf16 v[74:77], v[98:101], v[54:57], v[74:77]
	ds_read_b128 v[98:101], v171 offset:4096
	ds_read_b128 v[138:141], v171 offset:6144
	s_waitcnt lgkmcnt(0)
	ds_read2_b64 v[212:215], v172 offset1:4
	ds_read2_b64 v[216:219], v172 offset0:8 offset1:12
	ds_read2_b64 v[244:247], v173 offset0:32 offset1:36
	ds_read2_b64 v[248:251], v173 offset0:40 offset1:44
	v_mfma_f32_16x16x32_bf16 v[86:89], v[82:85], v[46:49], v[152:155]
	v_mfma_f32_16x16x32_bf16 v[82:85], v[82:85], v[50:53], v[156:159]
	v_mfma_f32_16x16x32_bf16 v[102:105], v[98:101], v[42:45], v[86:89]
	v_mfma_f32_16x16x32_bf16 v[86:89], v[98:101], v[54:57], v[82:85]
	v_mfma_f32_16x16x32_bf16 v[82:85], v[134:137], v[46:49], v[152:155]
	v_mfma_f32_16x16x32_bf16 v[98:101], v[138:141], v[42:45], v[82:85]
	v_mfma_f32_16x16x32_bf16 v[82:85], v[134:137], v[50:53], v[156:159]
	v_mfma_f32_16x16x32_bf16 v[82:85], v[138:141], v[54:57], v[82:85]
	s_setprio 0
	v_max3_f32 v118, v94, v95, v96
	v_max3_f32 v119, v97, v90, v91
	v_max3_f32 v118, v118, v92, v93
	v_max3_f32 v118, v118, v119, v102
	v_max3_f32 v119, v103, v104, v105
	v_max3_f32 v118, v118, v119, v98
	v_max3_f32 v119, v99, v100, v101
	v_max_f32_e32 v118, v118, v119
	v_mov_b32_e32 v119, v118
	s_nop 1
	v_permlane16_swap_b32_e32 v119, v118
	v_max_f32_e32 v118, v118, v119
	v_mov_b32_e32 v119, v118
	s_nop 1
	v_permlane32_swap_b32_e32 v119, v118
	v_max_f32_e32 v118, v118, v119
	v_cmp_lt_f32_e32 vcc, 0x41000000, v118
	s_cbranch_vccz .LBB0_1277
	v_max_f32_e32 v119, 0, v118
	v_add_f32_e32 v124, v122, v119
	v_exp_f32_e64 v118, -v119
	v_mov_b32_e32 v125, v123
	v_mov_b32_e32 v122, v124
	v_xor_b32_e32 v152, 0x80000000, v124
	v_mov_b32_e32 v153, v152
	v_mov_b32_e32 v154, v152
	v_mov_b32_e32 v155, v152
	v_sub_f32_e32 v94, v94, v119
	v_sub_f32_e32 v95, v95, v119
	v_sub_f32_e32 v96, v96, v119
	v_sub_f32_e32 v97, v97, v119
	v_sub_f32_e32 v90, v90, v119
	v_sub_f32_e32 v91, v91, v119
	v_sub_f32_e32 v92, v92, v119
	v_sub_f32_e32 v93, v93, v119
	v_sub_f32_e32 v102, v102, v119
	v_sub_f32_e32 v103, v103, v119
	v_sub_f32_e32 v104, v104, v119
	v_sub_f32_e32 v105, v105, v119
	v_sub_f32_e32 v98, v98, v119
	v_sub_f32_e32 v99, v99, v119
	v_sub_f32_e32 v100, v100, v119
	v_sub_f32_e32 v101, v101, v119
	v_pk_mul_f32 v[38:39], v[38:39], v[118:119] op_sel_hi:[1,0]
	v_pk_mul_f32 v[40:41], v[40:41], v[118:119] op_sel_hi:[1,0]
	v_pk_mul_f32 v[32:33], v[32:33], v[118:119] op_sel_hi:[1,0]
	v_pk_mul_f32 v[30:31], v[30:31], v[118:119] op_sel_hi:[1,0]
	v_pk_mul_f32 v[24:25], v[24:25], v[118:119] op_sel_hi:[1,0]
	v_pk_mul_f32 v[22:23], v[22:23], v[118:119] op_sel_hi:[1,0]
	v_pk_mul_f32 v[12:13], v[12:13], v[118:119] op_sel_hi:[1,0]
	v_pk_mul_f32 v[10:11], v[10:11], v[118:119] op_sel_hi:[1,0]
	v_pk_mul_f32 v[8:9], v[8:9], v[118:119] op_sel_hi:[1,0]
	v_pk_mul_f32 v[6:7], v[6:7], v[118:119] op_sel_hi:[1,0]
	s_branch .LBB0_1278

.LBB0_1280:
	v_mov_b64_e32 v[118:119], v[124:125]
	v_exp_f32_e32 v94, v94
	v_exp_f32_e32 v95, v95
	v_exp_f32_e32 v96, v96
	v_exp_f32_e32 v97, v97
	v_exp_f32_e32 v90, v90
	v_exp_f32_e32 v91, v91
	v_exp_f32_e32 v92, v92
	v_exp_f32_e32 v93, v93
	v_cvt_pk_bf16_f32 v160, v94, v95
	v_cvt_pk_bf16_f32 v161, v96, v97
	v_cvt_pk_bf16_f32 v162, v90, v91
	v_cvt_pk_bf16_f32 v163, v92, v93
	s_setprio 1
	s_waitcnt vmcnt(4)
	ds_write_b128 v180, v[58:61] offset:17408
	ds_write_b128 v182, v[62:65] offset:25600
	ds_write_b128 v181, v[66:69] offset:17408
	ds_write_b128 v182, v[70:73] offset:30208
	ds_read2_b64 v[94:97], v176 offset0:64 offset1:68
	v_mfma_f32_16x16x32_bf16 v[38:41], v[190:193], v[160:163], v[38:41]
	v_exp_f32_e32 v102, v102
	v_exp_f32_e32 v103, v103
	v_mfma_f32_16x16x32_bf16 v[30:33], v[212:215], v[160:163], v[30:33]
	v_exp_f32_e32 v104, v104
	v_exp_f32_e32 v105, v105
	v_mfma_f32_16x16x32_bf16 v[22:25], v[244:247], v[160:163], v[22:25]
	v_exp_f32_e32 v98, v98
	v_exp_f32_e32 v99, v99
	s_waitcnt lgkmcnt(0)
	v_mfma_f32_16x16x32_bf16 v[10:13], v[94:97], v[160:163], v[10:13]
	v_exp_f32_e32 v100, v100
	v_exp_f32_e32 v101, v101
	v_cvt_pk_bf16_f32 v166, v102, v103
	v_cvt_pk_bf16_f32 v167, v104, v105
	v_cvt_pk_bf16_f32 v168, v98, v99
	v_cvt_pk_bf16_f32 v169, v100, v101
	ds_read2_b64 v[98:101], v176 offset0:72 offset1:76
	ds_read2_b64 v[102:105], v177 offset0:96 offset1:100
	v_mfma_f32_16x16x32_bf16 v[38:41], v[190:193], v[166:169], v[38:41]
	v_exp_f32_e32 v134, v74
	v_exp_f32_e32 v135, v75
	v_mfma_f32_16x16x32_bf16 v[30:33], v[216:219], v[166:169], v[30:33]
	v_exp_f32_e32 v136, v76
	v_exp_f32_e32 v137, v77
	v_mfma_f32_16x16x32_bf16 v[22:25], v[248:251], v[166:169], v[22:25]
	v_exp_f32_e32 v138, v86
	v_exp_f32_e32 v139, v87
	s_waitcnt lgkmcnt(0)
	v_mfma_f32_16x16x32_bf16 v[6:9], v[102:105], v[160:163], v[6:9]
	v_exp_f32_e32 v140, v88
	v_exp_f32_e32 v141, v89
	v_mfma_f32_16x16x32_bf16 v[10:13], v[98:101], v[166:169], v[10:13]
	v_exp_f32_e32 v122, v78
	v_exp_f32_e32 v123, v79
	v_cvt_pk_bf16_f32 v88, v134, v135
	v_cvt_pk_bf16_f32 v89, v136, v137
	ds_read2_b64 v[134:137], v177 offset0:104 offset1:108
	v_exp_f32_e32 v124, v80
	v_exp_f32_e32 v133, v81
	v_cvt_pk_bf16_f32 v86, v122, v123
	v_cvt_pk_bf16_f32 v87, v124, v133
	s_nop 1
	v_mfma_f32_16x16x32_bf16 v[34:37], v[190:193], v[86:89], v[34:37]
	v_exp_f32_e32 v142, v82
	v_exp_f32_e32 v143, v83
	v_mfma_f32_16x16x32_bf16 v[26:29], v[212:215], v[86:89], v[26:29]
	v_exp_f32_e32 v144, v84
	v_exp_f32_e32 v125, v85
	v_mfma_f32_16x16x32_bf16 v[18:21], v[244:247], v[86:89], v[18:21]
	v_cvt_pk_bf16_f32 v90, v138, v139
	v_cvt_pk_bf16_f32 v91, v140, v141
	v_mfma_f32_16x16x32_bf16 v[14:17], v[94:97], v[86:89], v[14:17]
	v_cvt_pk_bf16_f32 v92, v142, v143
	v_cvt_pk_bf16_f32 v93, v144, v125
	v_mfma_f32_16x16x32_bf16 v[2:5], v[102:105], v[86:89], v[2:5]
	s_add_i32 s1, s0, 2
	s_min_u32 s1, s1, 0x43
	s_lshl_b32 s2, s1, 14
	s_lshl_b32 s56, s1, 7
	v_lshl_add_u64 v[58:59], v[184:185], 0, s[2:3]
	v_lshl_add_u64 v[66:67], v[120:121], 0, s[56:57]
	v_lshl_add_u64 v[68:69], v[186:187], 0, s[2:3]
	v_lshl_add_u64 v[70:71], v[188:189], 0, s[56:57]
	v_mfma_f32_16x16x32_bf16 v[34:37], v[190:193], v[90:93], v[34:37]
	global_load_dwordx4 v[58:61], v[58:59], off
	v_mfma_f32_16x16x32_bf16 v[26:29], v[216:219], v[90:93], v[26:29]
	global_load_dwordx4 v[62:65], v[66:67], off
	v_mfma_f32_16x16x32_bf16 v[18:21], v[248:251], v[90:93], v[18:21]
	global_load_dwordx4 v[66:69], v[68:69], off
	v_mfma_f32_16x16x32_bf16 v[14:17], v[98:101], v[90:93], v[14:17]
	global_load_dwordx4 v[70:73], v[70:71], off
	s_waitcnt lgkmcnt(0)
	v_mfma_f32_16x16x32_bf16 v[6:9], v[134:137], v[166:169], v[6:9]
	v_mfma_f32_16x16x32_bf16 v[2:5], v[134:137], v[90:93], v[2:5]
	s_setprio 0
	s_cmpk_lg_i32 s0, 0x43
	s_waitcnt lgkmcnt(0)
	s_barrier
	s_cbranch_scc0 .LBB0_1282
	v_mov_b64_e32 v[122:123], v[118:119]
	s_branch .Lga_odd
.Lga_odd:
	s_add_i32 s0, s0, 1
	ds_read_b128 v[74:77], v170 offset:17408
	ds_read_b128 v[82:85], v170 offset:19456
	ds_read_b128 v[86:89], v171 offset:17408
	ds_read_b128 v[98:101], v171 offset:19456
	s_setprio 1
	s_waitcnt lgkmcnt(0)
	v_mfma_f32_16x16x32_bf16 v[78:81], v[74:77], v[46:49], v[152:155]
	v_mfma_f32_16x16x32_bf16 v[74:77], v[74:77], v[50:53], v[156:159]
	v_mfma_f32_16x16x32_bf16 v[94:97], v[86:89], v[42:45], v[78:81]
	v_mfma_f32_16x16x32_bf16 v[78:81], v[86:89], v[54:57], v[74:77]
	v_mfma_f32_16x16x32_bf16 v[74:77], v[82:85], v[46:49], v[152:155]
	v_mfma_f32_16x16x32_bf16 v[90:93], v[98:101], v[42:45], v[74:77]
	v_mfma_f32_16x16x32_bf16 v[74:77], v[82:85], v[50:53], v[156:159]
	ds_read_b128 v[82:85], v170 offset:21504
	ds_read_b128 v[134:137], v170 offset:23552
	v_mfma_f32_16x16x32_bf16 v[74:77], v[98:101], v[54:57], v[74:77]
	ds_read_b128 v[98:101], v171 offset:21504
	ds_read_b128 v[138:141], v171 offset:23552
	s_waitcnt lgkmcnt(0)
	ds_read2_b64 v[212:215], v174 offset1:4
	ds_read2_b64 v[216:219], v174 offset0:8 offset1:12
	ds_read2_b64 v[244:247], v175 offset0:32 offset1:36
	ds_read2_b64 v[248:251], v175 offset0:40 offset1:44
	v_mfma_f32_16x16x32_bf16 v[86:89], v[82:85], v[46:49], v[152:155]
	v_mfma_f32_16x16x32_bf16 v[82:85], v[82:85], v[50:53], v[156:159]
	v_mfma_f32_16x16x32_bf16 v[102:105], v[98:101], v[42:45], v[86:89]
	v_mfma_f32_16x16x32_bf16 v[86:89], v[98:101], v[54:57], v[82:85]
	v_mfma_f32_16x16x32_bf16 v[82:85], v[134:137], v[46:49], v[152:155]
	v_mfma_f32_16x16x32_bf16 v[98:101], v[138:141], v[42:45], v[82:85]
	v_mfma_f32_16x16x32_bf16 v[82:85], v[134:137], v[50:53], v[156:159]
	v_mfma_f32_16x16x32_bf16 v[82:85], v[138:141], v[54:57], v[82:85]
	s_setprio 0
	v_max3_f32 v118, v94, v95, v96
	v_max3_f32 v119, v97, v90, v91
	v_max3_f32 v118, v118, v92, v93
	v_max3_f32 v118, v118, v119, v102
	v_max3_f32 v119, v103, v104, v105
	v_max3_f32 v118, v118, v119, v98
	v_max3_f32 v119, v99, v100, v101
	v_max_f32_e32 v118, v118, v119
	v_mov_b32_e32 v119, v118
	s_nop 1
	v_permlane16_swap_b32_e32 v119, v118
	v_max_f32_e32 v118, v118, v119
	v_mov_b32_e32 v119, v118
	s_nop 1
	v_permlane32_swap_b32_e32 v119, v118
	v_max_f32_e32 v118, v118, v119
	v_cmp_lt_f32_e32 vcc, 0x41000000, v118
	s_cbranch_vccz .Lga_o_1277
	v_max_f32_e32 v119, 0, v118
	v_add_f32_e32 v124, v122, v119
	v_exp_f32_e64 v118, -v119
	v_mov_b32_e32 v125, v123
	v_mov_b32_e32 v122, v124
	v_xor_b32_e32 v152, 0x80000000, v124
	v_mov_b32_e32 v153, v152
	v_mov_b32_e32 v154, v152
	v_mov_b32_e32 v155, v152
	v_sub_f32_e32 v94, v94, v119
	v_sub_f32_e32 v95, v95, v119
	v_sub_f32_e32 v96, v96, v119
	v_sub_f32_e32 v97, v97, v119
	v_sub_f32_e32 v90, v90, v119
	v_sub_f32_e32 v91, v91, v119
	v_sub_f32_e32 v92, v92, v119
	v_sub_f32_e32 v93, v93, v119
	v_sub_f32_e32 v102, v102, v119
	v_sub_f32_e32 v103, v103, v119
	v_sub_f32_e32 v104, v104, v119
	v_sub_f32_e32 v105, v105, v119
	v_sub_f32_e32 v98, v98, v119
	v_sub_f32_e32 v99, v99, v119
	v_sub_f32_e32 v100, v100, v119
	v_sub_f32_e32 v101, v101, v119
	v_pk_mul_f32 v[38:39], v[38:39], v[118:119] op_sel_hi:[1,0]
	v_pk_mul_f32 v[40:41], v[40:41], v[118:119] op_sel_hi:[1,0]
	v_pk_mul_f32 v[32:33], v[32:33], v[118:119] op_sel_hi:[1,0]
	v_pk_mul_f32 v[30:31], v[30:31], v[118:119] op_sel_hi:[1,0]
	v_pk_mul_f32 v[24:25], v[24:25], v[118:119] op_sel_hi:[1,0]
	v_pk_mul_f32 v[22:23], v[22:23], v[118:119] op_sel_hi:[1,0]
	v_pk_mul_f32 v[12:13], v[12:13], v[118:119] op_sel_hi:[1,0]
	v_pk_mul_f32 v[10:11], v[10:11], v[118:119] op_sel_hi:[1,0]
	v_pk_mul_f32 v[8:9], v[8:9], v[118:119] op_sel_hi:[1,0]
	v_pk_mul_f32 v[6:7], v[6:7], v[118:119] op_sel_hi:[1,0]
	s_branch .Lga_o_1278

.Lga_o_1280:
	v_mov_b64_e32 v[118:119], v[124:125]
	v_exp_f32_e32 v94, v94
	v_exp_f32_e32 v95, v95
	v_exp_f32_e32 v96, v96
	v_exp_f32_e32 v97, v97
	v_exp_f32_e32 v90, v90
	v_exp_f32_e32 v91, v91
	v_exp_f32_e32 v92, v92
	v_exp_f32_e32 v93, v93
	v_cvt_pk_bf16_f32 v160, v94, v95
	v_cvt_pk_bf16_f32 v161, v96, v97
	v_cvt_pk_bf16_f32 v162, v90, v91
	v_cvt_pk_bf16_f32 v163, v92, v93
	s_setprio 1
	s_waitcnt vmcnt(4)
	ds_write_b128 v180, v[228:231]
	ds_write_b128 v182, v[232:235] offset:8192
	ds_write_b128 v181, v[236:239]
	ds_write_b128 v182, v[240:243] offset:12800
	ds_read2_b64 v[94:97], v178 offset0:64 offset1:68
	v_mfma_f32_16x16x32_bf16 v[38:41], v[190:193], v[160:163], v[38:41]
	v_exp_f32_e32 v102, v102
	v_exp_f32_e32 v103, v103
	v_mfma_f32_16x16x32_bf16 v[30:33], v[212:215], v[160:163], v[30:33]
	v_exp_f32_e32 v104, v104
	v_exp_f32_e32 v105, v105
	v_mfma_f32_16x16x32_bf16 v[22:25], v[244:247], v[160:163], v[22:25]
	v_exp_f32_e32 v98, v98
	v_exp_f32_e32 v99, v99
	s_waitcnt lgkmcnt(0)
	v_mfma_f32_16x16x32_bf16 v[10:13], v[94:97], v[160:163], v[10:13]
	v_exp_f32_e32 v100, v100
	v_exp_f32_e32 v101, v101
	v_cvt_pk_bf16_f32 v166, v102, v103
	v_cvt_pk_bf16_f32 v167, v104, v105
	v_cvt_pk_bf16_f32 v168, v98, v99
	v_cvt_pk_bf16_f32 v169, v100, v101
	ds_read2_b64 v[98:101], v178 offset0:72 offset1:76
	ds_read2_b64 v[102:105], v179 offset0:96 offset1:100
	v_mfma_f32_16x16x32_bf16 v[38:41], v[190:193], v[166:169], v[38:41]
	v_exp_f32_e32 v134, v74
	v_exp_f32_e32 v135, v75
	v_mfma_f32_16x16x32_bf16 v[30:33], v[216:219], v[166:169], v[30:33]
	v_exp_f32_e32 v136, v76
	v_exp_f32_e32 v137, v77
	v_mfma_f32_16x16x32_bf16 v[22:25], v[248:251], v[166:169], v[22:25]
	v_exp_f32_e32 v138, v86
	v_exp_f32_e32 v139, v87
	s_waitcnt lgkmcnt(0)
	v_mfma_f32_16x16x32_bf16 v[6:9], v[102:105], v[160:163], v[6:9]
	v_exp_f32_e32 v140, v88
	v_exp_f32_e32 v141, v89
	v_mfma_f32_16x16x32_bf16 v[10:13], v[98:101], v[166:169], v[10:13]
	v_exp_f32_e32 v122, v78
	v_exp_f32_e32 v123, v79
	v_cvt_pk_bf16_f32 v88, v134, v135
	v_cvt_pk_bf16_f32 v89, v136, v137
	ds_read2_b64 v[134:137], v179 offset0:104 offset1:108
	v_exp_f32_e32 v124, v80
	v_exp_f32_e32 v133, v81
	v_cvt_pk_bf16_f32 v86, v122, v123
	v_cvt_pk_bf16_f32 v87, v124, v133
	s_nop 1
	v_mfma_f32_16x16x32_bf16 v[34:37], v[190:193], v[86:89], v[34:37]
	v_exp_f32_e32 v142, v82
	v_exp_f32_e32 v143, v83
	v_mfma_f32_16x16x32_bf16 v[26:29], v[212:215], v[86:89], v[26:29]
	v_exp_f32_e32 v144, v84
	v_exp_f32_e32 v125, v85
	v_mfma_f32_16x16x32_bf16 v[18:21], v[244:247], v[86:89], v[18:21]
	v_cvt_pk_bf16_f32 v90, v138, v139
	v_cvt_pk_bf16_f32 v91, v140, v141
	v_mfma_f32_16x16x32_bf16 v[14:17], v[94:97], v[86:89], v[14:17]
	v_cvt_pk_bf16_f32 v92, v142, v143
	v_cvt_pk_bf16_f32 v93, v144, v125
	v_mfma_f32_16x16x32_bf16 v[2:5], v[102:105], v[86:89], v[2:5]
	s_add_i32 s1, s0, 2
	s_min_u32 s1, s1, 0x43
	s_lshl_b32 s2, s1, 14
	s_lshl_b32 s56, s1, 7
	v_lshl_add_u64 v[228:229], v[184:185], 0, s[2:3]
	v_lshl_add_u64 v[236:237], v[120:121], 0, s[56:57]
	v_lshl_add_u64 v[238:239], v[186:187], 0, s[2:3]
	v_lshl_add_u64 v[240:241], v[188:189], 0, s[56:57]
	v_mfma_f32_16x16x32_bf16 v[34:37], v[190:193], v[90:93], v[34:37]
	global_load_dwordx4 v[228:231], v[228:229], off
	v_mfma_f32_16x16x32_bf16 v[26:29], v[216:219], v[90:93], v[26:29]
	global_load_dwordx4 v[232:235], v[236:237], off
	v_mfma_f32_16x16x32_bf16 v[18:21], v[248:251], v[90:93], v[18:21]
	global_load_dwordx4 v[236:239], v[238:239], off
	v_mfma_f32_16x16x32_bf16 v[14:17], v[98:101], v[90:93], v[14:17]
	global_load_dwordx4 v[240:243], v[240:241], off
	s_waitcnt lgkmcnt(0)
	v_mfma_f32_16x16x32_bf16 v[6:9], v[134:137], v[166:169], v[6:9]
	v_mfma_f32_16x16x32_bf16 v[2:5], v[134:137], v[90:93], v[2:5]
	s_setprio 0
	s_cmpk_lg_i32 s0, 0x43
	s_waitcnt lgkmcnt(0)
	s_barrier
	s_cbranch_scc0 .LBB0_1282
	v_mov_b64_e32 v[122:123], v[118:119]
	s_branch .LBB0_1275
